# code placement: one 4-byte pad ahead of the prompt-attention tile loop (loop head moved from byte phase 4 to 0 mod 8)
# baseline (speedup 1.0000x reference)
;     ...
;         gload(0); lstore(0); if (ntiles > 1) gload(1);
;         __syncthreads();
;         for (int t = 0; t < ntiles; ++t) { const int cur = t & 1;
.LBB0_1906:
	s_nop 0
	s_lshl_b32 s0, s15, 2
	v_ashrrev_i32_e32 v185, 31, v184
	v_mul_u32_u24_e32 v14, 0x88, v208
	s_add_i32 s13, s13, 5
	s_add_i32 s46, s16, 0x80
	s_sub_i32 s15, 0, s0
	s_movk_i32 s16, 0xff80
	s_waitcnt lgkmcnt(0)
	s_barrier
